# gemm_out K loop: LDS-DMA destinations formed with scalar adds as well; its loop header 40 bytes past a 256-byte boundary
# baseline (speedup 1.0000x reference)
.LBB0_60:
	s_or_b64 exec, exec, s[10:11]
	v_mov_b32_e32 v2, s8
	s_waitcnt lgkmcnt(0)
	s_barrier
	ds_read_b32 v2, v2
	s_waitcnt lgkmcnt(0)
	v_readfirstlane_b32 s2, v2
	s_ashr_i32 s10, s2, 3
	s_and_b32 s10, s10, -8
	s_or_b32 s12, s10, s48
	s_cmp_gt_i32 s12, 39
	s_mov_b64 s[10:11], -1
	s_cbranch_scc1 .LBB0_55
	s_lshl_b32 s11, s2, 7
	s_lshl_b32 s10, s12, 10
	s_and_b32 s11, s11, 0x380
	s_or_b32 s13, s10, s11
	s_bfe_u32 s12, s2, 0x30003
	s_lshl_b32 s49, s12, 7
	s_mul_i32 s10, s13, 0x1820
	s_mul_hi_i32 s2, s13, 0x1820
	s_add_u32 s10, s34, s10
	s_addc_u32 s11, s35, s2
	s_lshl_b32 s2, s12, 18
	v_readlane_b32 s42, v246, 23
	s_add_u32 s42, s42, s2
	v_readlane_b32 s43, v246, 24
	v_readfirstlane_b32 s56, v1
	v_add_u32_e32 v6, 0x4000, v1
	s_waitcnt lgkmcnt(0)
	s_barrier
	s_addc_u32 s43, s43, 0
	v_lshl_add_u64 v[2:3], v[66:67], 1, s[10:11]
	s_mov_b32 m0, s56
	v_readfirstlane_b32 s57, v6
	v_add_u32_e32 v8, 0x1000, v1
	global_load_lds_dwordx4 v[2:3], off
	v_lshl_add_u64 v[4:5], v[68:69], 1, s[42:43]
	s_mov_b32 m0, s57
	v_readfirstlane_b32 s58, v8
	v_add_u32_e32 v10, 0x5000, v1
	global_load_lds_dwordx4 v[4:5], off
	v_lshl_add_u64 v[6:7], v[70:71], 1, s[10:11]
	s_mov_b32 m0, s58
	v_readfirstlane_b32 s59, v10
	v_add_u32_e32 v12, 0x2000, v1
	global_load_lds_dwordx4 v[6:7], off
	v_lshl_add_u64 v[8:9], v[72:73], 1, s[42:43]
	s_mov_b32 m0, s59
	v_readfirstlane_b32 s60, v12
	v_add_u32_e32 v14, 0x6000, v1
	global_load_lds_dwordx4 v[8:9], off
	v_lshl_add_u64 v[10:11], v[74:75], 1, s[10:11]
	s_mov_b32 m0, s60
	v_readfirstlane_b32 s61, v14
	v_add_u32_e32 v16, 0x3000, v1
	global_load_lds_dwordx4 v[10:11], off
	v_lshl_add_u64 v[12:13], v[76:77], 1, s[42:43]
	s_mov_b32 m0, s61
	v_readfirstlane_b32 s97, v16
	v_add_u32_e32 v18, 0x7000, v1
	global_load_lds_dwordx4 v[12:13], off
	v_lshl_add_u64 v[14:15], v[78:79], 1, s[10:11]
	s_mov_b32 m0, s97
	v_readfirstlane_b32 s44, v18
	global_load_lds_dwordx4 v[14:15], off
	v_lshl_add_u64 v[16:17], v[80:81], 1, s[42:43]
	s_mov_b32 m0, s44
	v_add_u32_e32 v20, 0x8000, v1
	global_load_lds_dwordx4 v[16:17], off
	s_waitcnt vmcnt(0)
	v_readfirstlane_b32 s42, v20
	v_add_u32_e32 v20, 0xc000, v1
	s_waitcnt lgkmcnt(0)
	s_barrier
	v_lshl_add_u64 v[18:19], v[2:3], 0, s[98:99]
	s_mov_b32 m0, s42
	v_readfirstlane_b32 s43, v20
	v_add_u32_e32 v20, 0x9000, v1
	global_load_lds_dwordx4 v[18:19], off
	v_lshl_add_u64 v[18:19], v[4:5], 0, s[98:99]
	s_mov_b32 m0, s43
	v_readfirstlane_b32 s50, v20
	v_add_u32_e32 v20, 0xd000, v1
	global_load_lds_dwordx4 v[18:19], off
	v_lshl_add_u64 v[18:19], v[6:7], 0, s[98:99]
	s_mov_b32 m0, s50
	v_readfirstlane_b32 s51, v20
	v_add_u32_e32 v20, 0xa000, v1
	global_load_lds_dwordx4 v[18:19], off
	v_lshl_add_u64 v[18:19], v[8:9], 0, s[98:99]
	s_mov_b32 m0, s51
	v_readfirstlane_b32 s52, v20
	v_add_u32_e32 v20, 0xe000, v1
	global_load_lds_dwordx4 v[18:19], off
	v_lshl_add_u64 v[18:19], v[10:11], 0, s[98:99]
	s_mov_b32 m0, s52
	v_readfirstlane_b32 s53, v20
	v_add_u32_e32 v20, 0xb000, v1
	global_load_lds_dwordx4 v[18:19], off
	v_lshl_add_u64 v[18:19], v[12:13], 0, s[98:99]
	s_mov_b32 m0, s53
	v_readfirstlane_b32 s54, v20
	v_add_u32_e32 v20, 0xf000, v1
	global_load_lds_dwordx4 v[18:19], off
	v_lshl_add_u64 v[18:19], v[14:15], 0, s[98:99]
	s_mov_b32 m0, s54
	v_readfirstlane_b32 s55, v20
	global_load_lds_dwordx4 v[18:19], off
	v_lshl_add_u64 v[18:19], v[16:17], 0, s[98:99]
	s_mov_b32 m0, s55
	s_mov_b64 vcc, 0x100
	global_load_lds_dwordx4 v[18:19], off
	v_add_u32_e32 v19, v102, v104
	ds_read_b128 v[20:23], v19 offset:16384
	ds_read_b128 v[32:35], v19 offset:18432
	ds_read_b128 v[40:43], v19 offset:20480
	ds_read_b128 v[126:129], v19 offset:19456
	ds_read_b128 v[48:51], v19 offset:22528
	ds_read_b128 v[130:133], v19 offset:21504
	v_add_u32_e32 v18, v102, v103
	ds_read_b128 v[24:27], v18
	ds_read_b128 v[52:55], v18 offset:2048
	ds_read_b128 v[98:101], v18 offset:4096
	ds_read_b128 v[118:121], v18 offset:6144
	ds_read_b128 v[122:125], v19 offset:17408
	ds_read_b128 v[134:137], v19 offset:23552
	s_waitcnt lgkmcnt(0)
	v_mfma_f32_16x16x32_bf16 v[28:31], v[20:23], v[24:27], 0
	v_lshl_add_u64 v[64:65], v[2:3], 0, vcc
	s_mov_b32 m0, s56
	s_mov_b64 s[62:63], 0x180
	v_mfma_f32_16x16x32_bf16 v[36:39], v[32:35], v[24:27], 0
	v_mfma_f32_16x16x32_bf16 v[44:47], v[40:43], v[24:27], 0
	v_mfma_f32_16x16x32_bf16 v[24:27], v[48:51], v[24:27], 0
	v_mfma_f32_16x16x32_bf16 v[56:59], v[20:23], v[52:55], 0
	v_mfma_f32_16x16x32_bf16 v[60:63], v[32:35], v[52:55], 0
	v_mfma_f32_16x16x32_bf16 v[94:97], v[40:43], v[52:55], 0
	v_mfma_f32_16x16x32_bf16 v[52:55], v[48:51], v[52:55], 0
	v_mfma_f32_16x16x32_bf16 v[106:109], v[20:23], v[98:101], 0
	v_mfma_f32_16x16x32_bf16 v[110:113], v[32:35], v[98:101], 0
	v_mfma_f32_16x16x32_bf16 v[114:117], v[40:43], v[98:101], 0
	v_mfma_f32_16x16x32_bf16 v[98:101], v[48:51], v[98:101], 0
	v_mfma_f32_16x16x32_bf16 v[20:23], v[20:23], v[118:121], 0
	v_mfma_f32_16x16x32_bf16 v[32:35], v[32:35], v[118:121], 0
	v_mfma_f32_16x16x32_bf16 v[40:43], v[40:43], v[118:121], 0
	v_mfma_f32_16x16x32_bf16 v[48:51], v[48:51], v[118:121], 0
	ds_read_b128 v[118:121], v18 offset:1024
	s_waitcnt lgkmcnt(0)
	v_mfma_f32_16x16x32_bf16 v[28:31], v[122:125], v[118:121], v[28:31]
	v_mfma_f32_16x16x32_bf16 v[36:39], v[126:129], v[118:121], v[36:39]
	v_mfma_f32_16x16x32_bf16 v[44:47], v[130:133], v[118:121], v[44:47]
	v_mfma_f32_16x16x32_bf16 v[24:27], v[134:137], v[118:121], v[24:27]
	ds_read_b128 v[118:121], v18 offset:3072
	s_waitcnt lgkmcnt(0)
	v_mfma_f32_16x16x32_bf16 v[56:59], v[122:125], v[118:121], v[56:59]
	v_mfma_f32_16x16x32_bf16 v[60:63], v[126:129], v[118:121], v[60:63]
	v_mfma_f32_16x16x32_bf16 v[94:97], v[130:133], v[118:121], v[94:97]
	v_mfma_f32_16x16x32_bf16 v[52:55], v[134:137], v[118:121], v[52:55]
	ds_read_b128 v[118:121], v18 offset:5120
	s_waitcnt lgkmcnt(0)
	v_mfma_f32_16x16x32_bf16 v[106:109], v[122:125], v[118:121], v[106:109]
	v_mfma_f32_16x16x32_bf16 v[110:113], v[126:129], v[118:121], v[110:113]
	v_mfma_f32_16x16x32_bf16 v[114:117], v[130:133], v[118:121], v[114:117]
	v_mfma_f32_16x16x32_bf16 v[98:101], v[134:137], v[118:121], v[98:101]
	ds_read_b128 v[118:121], v18 offset:7168
	s_waitcnt vmcnt(0)
	s_waitcnt lgkmcnt(0)
	s_barrier
	global_load_lds_dwordx4 v[64:65], off
	v_lshl_add_u64 v[64:65], v[4:5], 0, vcc
	s_mov_b32 m0, s57
	s_waitcnt lgkmcnt(0)
	v_mfma_f32_16x16x32_bf16 v[20:23], v[122:125], v[118:121], v[20:23]
	global_load_lds_dwordx4 v[64:65], off
	v_lshl_add_u64 v[64:65], v[6:7], 0, vcc
	s_mov_b32 m0, s58
	v_mfma_f32_16x16x32_bf16 v[32:35], v[126:129], v[118:121], v[32:35]
	global_load_lds_dwordx4 v[64:65], off
	v_lshl_add_u64 v[64:65], v[8:9], 0, vcc
	s_mov_b32 m0, s59
	v_mfma_f32_16x16x32_bf16 v[40:43], v[130:133], v[118:121], v[40:43]
	global_load_lds_dwordx4 v[64:65], off
	v_lshl_add_u64 v[64:65], v[10:11], 0, vcc
	s_mov_b32 m0, s60
	v_mfma_f32_16x16x32_bf16 v[48:51], v[134:137], v[118:121], v[48:51]
	global_load_lds_dwordx4 v[64:65], off
	v_lshl_add_u64 v[64:65], v[12:13], 0, vcc
	s_mov_b32 m0, s61
	s_nop 0
	global_load_lds_dwordx4 v[64:65], off
	v_lshl_add_u64 v[64:65], v[14:15], 0, vcc
	s_mov_b32 m0, s97
	s_nop 0
	global_load_lds_dwordx4 v[64:65], off
	v_lshl_add_u64 v[64:65], v[16:17], 0, vcc
	s_mov_b32 m0, s44
	s_nop 0
	global_load_lds_dwordx4 v[64:65], off
	ds_read_b128 v[122:125], v19 offset:49152
	ds_read_b128 v[118:121], v18 offset:32768
	ds_read_b128 v[126:129], v19 offset:51200
	ds_read_b128 v[130:133], v19 offset:53248
	ds_read_b128 v[134:137], v19 offset:55296
	s_waitcnt lgkmcnt(0)
	v_mfma_f32_16x16x32_bf16 v[28:31], v[122:125], v[118:121], v[28:31]
	v_lshl_add_u64 v[64:65], v[2:3], 0, s[62:63]
	s_mov_b32 m0, s42
	v_mfma_f32_16x16x32_bf16 v[36:39], v[126:129], v[118:121], v[36:39]
	v_mfma_f32_16x16x32_bf16 v[44:47], v[130:133], v[118:121], v[44:47]
	v_mfma_f32_16x16x32_bf16 v[24:27], v[134:137], v[118:121], v[24:27]
	ds_read_b128 v[118:121], v18 offset:34816
	s_waitcnt lgkmcnt(0)
	v_mfma_f32_16x16x32_bf16 v[56:59], v[122:125], v[118:121], v[56:59]
	v_mfma_f32_16x16x32_bf16 v[60:63], v[126:129], v[118:121], v[60:63]
	v_mfma_f32_16x16x32_bf16 v[94:97], v[130:133], v[118:121], v[94:97]
	v_mfma_f32_16x16x32_bf16 v[52:55], v[134:137], v[118:121], v[52:55]
	ds_read_b128 v[118:121], v18 offset:36864
	s_waitcnt lgkmcnt(0)
	v_mfma_f32_16x16x32_bf16 v[106:109], v[122:125], v[118:121], v[106:109]
	v_mfma_f32_16x16x32_bf16 v[110:113], v[126:129], v[118:121], v[110:113]
	v_mfma_f32_16x16x32_bf16 v[114:117], v[130:133], v[118:121], v[114:117]
	v_mfma_f32_16x16x32_bf16 v[98:101], v[134:137], v[118:121], v[98:101]
	ds_read_b128 v[118:121], v18 offset:38912
	s_waitcnt lgkmcnt(0)
	v_mfma_f32_16x16x32_bf16 v[20:23], v[122:125], v[118:121], v[20:23]
	ds_read_b128 v[122:125], v19 offset:50176
	v_mfma_f32_16x16x32_bf16 v[32:35], v[126:129], v[118:121], v[32:35]
	ds_read_b128 v[126:129], v19 offset:52224
	v_mfma_f32_16x16x32_bf16 v[40:43], v[130:133], v[118:121], v[40:43]
	ds_read_b128 v[130:133], v19 offset:54272
	v_mfma_f32_16x16x32_bf16 v[48:51], v[134:137], v[118:121], v[48:51]
	ds_read_b128 v[134:137], v19 offset:56320
	ds_read_b128 v[118:121], v18 offset:33792
	s_waitcnt lgkmcnt(0)
	v_mfma_f32_16x16x32_bf16 v[28:31], v[122:125], v[118:121], v[28:31]
	v_mfma_f32_16x16x32_bf16 v[36:39], v[126:129], v[118:121], v[36:39]
	v_mfma_f32_16x16x32_bf16 v[44:47], v[130:133], v[118:121], v[44:47]
	v_mfma_f32_16x16x32_bf16 v[24:27], v[134:137], v[118:121], v[24:27]
	ds_read_b128 v[118:121], v18 offset:35840
	s_waitcnt lgkmcnt(0)
	v_mfma_f32_16x16x32_bf16 v[56:59], v[122:125], v[118:121], v[56:59]
	v_mfma_f32_16x16x32_bf16 v[60:63], v[126:129], v[118:121], v[60:63]
	v_mfma_f32_16x16x32_bf16 v[94:97], v[130:133], v[118:121], v[94:97]
	v_mfma_f32_16x16x32_bf16 v[52:55], v[134:137], v[118:121], v[52:55]
	ds_read_b128 v[118:121], v18 offset:37888
	s_waitcnt lgkmcnt(0)
	v_mfma_f32_16x16x32_bf16 v[106:109], v[122:125], v[118:121], v[106:109]
	v_mfma_f32_16x16x32_bf16 v[110:113], v[126:129], v[118:121], v[110:113]
	v_mfma_f32_16x16x32_bf16 v[114:117], v[130:133], v[118:121], v[114:117]
	v_mfma_f32_16x16x32_bf16 v[98:101], v[134:137], v[118:121], v[98:101]
	ds_read_b128 v[118:121], v18 offset:39936
	s_waitcnt vmcnt(0)
	s_waitcnt lgkmcnt(0)
	s_barrier
	global_load_lds_dwordx4 v[64:65], off
	v_lshl_add_u64 v[64:65], v[4:5], 0, s[62:63]
	s_mov_b32 m0, s43
	s_waitcnt lgkmcnt(0)
	v_mfma_f32_16x16x32_bf16 v[20:23], v[122:125], v[118:121], v[20:23]
	global_load_lds_dwordx4 v[64:65], off
	v_lshl_add_u64 v[64:65], v[6:7], 0, s[62:63]
	s_mov_b32 m0, s50
	v_mfma_f32_16x16x32_bf16 v[32:35], v[126:129], v[118:121], v[32:35]
	global_load_lds_dwordx4 v[64:65], off
	v_lshl_add_u64 v[64:65], v[8:9], 0, s[62:63]
	s_mov_b32 m0, s51
	v_mfma_f32_16x16x32_bf16 v[40:43], v[130:133], v[118:121], v[40:43]
	global_load_lds_dwordx4 v[64:65], off
	v_lshl_add_u64 v[64:65], v[10:11], 0, s[62:63]
	s_mov_b32 m0, s52
	v_mfma_f32_16x16x32_bf16 v[48:51], v[134:137], v[118:121], v[48:51]
	global_load_lds_dwordx4 v[64:65], off
	v_lshl_add_u64 v[64:65], v[12:13], 0, s[62:63]
	s_mov_b32 m0, s53
	s_nop 0
	global_load_lds_dwordx4 v[64:65], off
	v_lshl_add_u64 v[64:65], v[14:15], 0, s[62:63]
	s_mov_b32 m0, s54
	s_nop 0
	global_load_lds_dwordx4 v[64:65], off
	v_lshl_add_u64 v[64:65], v[16:17], 0, s[62:63]
	s_mov_b32 m0, s55
	s_nop 0
	global_load_lds_dwordx4 v[64:65], off
	ds_read_b128 v[122:125], v19 offset:16384
	ds_read_b128 v[118:121], v18
	ds_read_b128 v[126:129], v19 offset:18432
	ds_read_b128 v[130:133], v19 offset:20480
	ds_read_b128 v[134:137], v19 offset:22528
	s_waitcnt lgkmcnt(0)
	v_mfma_f32_16x16x32_bf16 v[28:31], v[122:125], v[118:121], v[28:31]
	v_lshl_add_u64 v[64:65], v[2:3], 0, s[94:95]
	s_mov_b32 m0, s56
	v_mfma_f32_16x16x32_bf16 v[36:39], v[126:129], v[118:121], v[36:39]
	v_mfma_f32_16x16x32_bf16 v[44:47], v[130:133], v[118:121], v[44:47]
	v_mfma_f32_16x16x32_bf16 v[24:27], v[134:137], v[118:121], v[24:27]
	ds_read_b128 v[118:121], v18 offset:2048
	s_waitcnt lgkmcnt(0)
	v_mfma_f32_16x16x32_bf16 v[56:59], v[122:125], v[118:121], v[56:59]
	v_mfma_f32_16x16x32_bf16 v[60:63], v[126:129], v[118:121], v[60:63]
	v_mfma_f32_16x16x32_bf16 v[94:97], v[130:133], v[118:121], v[94:97]
	v_mfma_f32_16x16x32_bf16 v[52:55], v[134:137], v[118:121], v[52:55]
	ds_read_b128 v[118:121], v18 offset:4096
	s_waitcnt lgkmcnt(0)
	v_mfma_f32_16x16x32_bf16 v[106:109], v[122:125], v[118:121], v[106:109]
	v_mfma_f32_16x16x32_bf16 v[110:113], v[126:129], v[118:121], v[110:113]
	v_mfma_f32_16x16x32_bf16 v[114:117], v[130:133], v[118:121], v[114:117]
	v_mfma_f32_16x16x32_bf16 v[98:101], v[134:137], v[118:121], v[98:101]
	ds_read_b128 v[118:121], v18 offset:6144
	s_waitcnt lgkmcnt(0)
	v_mfma_f32_16x16x32_bf16 v[20:23], v[122:125], v[118:121], v[20:23]
	ds_read_b128 v[122:125], v19 offset:17408
	v_mfma_f32_16x16x32_bf16 v[32:35], v[126:129], v[118:121], v[32:35]
	ds_read_b128 v[126:129], v19 offset:19456
	v_mfma_f32_16x16x32_bf16 v[40:43], v[130:133], v[118:121], v[40:43]
	ds_read_b128 v[130:133], v19 offset:21504
	v_mfma_f32_16x16x32_bf16 v[48:51], v[134:137], v[118:121], v[48:51]
	ds_read_b128 v[134:137], v19 offset:23552
	ds_read_b128 v[118:121], v18 offset:1024
	s_waitcnt lgkmcnt(0)
	v_mfma_f32_16x16x32_bf16 v[28:31], v[122:125], v[118:121], v[28:31]
	v_mfma_f32_16x16x32_bf16 v[36:39], v[126:129], v[118:121], v[36:39]
	v_mfma_f32_16x16x32_bf16 v[44:47], v[130:133], v[118:121], v[44:47]
	v_mfma_f32_16x16x32_bf16 v[24:27], v[134:137], v[118:121], v[24:27]
	ds_read_b128 v[118:121], v18 offset:3072
	s_waitcnt lgkmcnt(0)
	v_mfma_f32_16x16x32_bf16 v[56:59], v[122:125], v[118:121], v[56:59]
	v_mfma_f32_16x16x32_bf16 v[60:63], v[126:129], v[118:121], v[60:63]
	v_mfma_f32_16x16x32_bf16 v[94:97], v[130:133], v[118:121], v[94:97]
	v_mfma_f32_16x16x32_bf16 v[52:55], v[134:137], v[118:121], v[52:55]
	ds_read_b128 v[118:121], v18 offset:5120
	s_waitcnt lgkmcnt(0)
	v_mfma_f32_16x16x32_bf16 v[106:109], v[122:125], v[118:121], v[106:109]
	v_mfma_f32_16x16x32_bf16 v[110:113], v[126:129], v[118:121], v[110:113]
	v_mfma_f32_16x16x32_bf16 v[114:117], v[130:133], v[118:121], v[114:117]
	v_mfma_f32_16x16x32_bf16 v[98:101], v[134:137], v[118:121], v[98:101]
	ds_read_b128 v[118:121], v18 offset:7168
	s_waitcnt vmcnt(0)
	s_waitcnt lgkmcnt(0)
	s_barrier
	global_load_lds_dwordx4 v[64:65], off
	v_lshl_add_u64 v[64:65], v[4:5], 0, s[94:95]
	s_mov_b32 m0, s57
	s_waitcnt lgkmcnt(0)
	v_mfma_f32_16x16x32_bf16 v[20:23], v[122:125], v[118:121], v[20:23]
	global_load_lds_dwordx4 v[64:65], off
	v_lshl_add_u64 v[64:65], v[6:7], 0, s[94:95]
	s_mov_b32 m0, s58
	v_mfma_f32_16x16x32_bf16 v[32:35], v[126:129], v[118:121], v[32:35]
	global_load_lds_dwordx4 v[64:65], off
	v_lshl_add_u64 v[64:65], v[8:9], 0, s[94:95]
	s_mov_b32 m0, s59
	v_mfma_f32_16x16x32_bf16 v[40:43], v[130:133], v[118:121], v[40:43]
	global_load_lds_dwordx4 v[64:65], off
	v_lshl_add_u64 v[64:65], v[10:11], 0, s[94:95]
	s_mov_b32 m0, s60
	v_mfma_f32_16x16x32_bf16 v[48:51], v[134:137], v[118:121], v[48:51]
	global_load_lds_dwordx4 v[64:65], off
	v_lshl_add_u64 v[64:65], v[12:13], 0, s[94:95]
	s_mov_b32 m0, s61
	s_nop 0
	global_load_lds_dwordx4 v[64:65], off
	v_lshl_add_u64 v[64:65], v[14:15], 0, s[94:95]
	s_mov_b32 m0, s97
	s_nop 0
	global_load_lds_dwordx4 v[64:65], off
	v_lshl_add_u64 v[64:65], v[16:17], 0, s[94:95]
	s_mov_b32 m0, s44
	s_nop 0
	global_load_lds_dwordx4 v[64:65], off
	ds_read_b128 v[122:125], v19 offset:49152
	ds_read_b128 v[118:121], v18 offset:32768
	ds_read_b128 v[126:129], v19 offset:51200
	ds_read_b128 v[130:133], v19 offset:53248
	ds_read_b128 v[134:137], v19 offset:55296
	s_waitcnt lgkmcnt(0)
	v_mfma_f32_16x16x32_bf16 v[28:31], v[122:125], v[118:121], v[28:31]
	v_lshl_add_u64 v[64:65], v[2:3], 0, s[36:37]
	s_mov_b32 m0, s42
	v_mfma_f32_16x16x32_bf16 v[36:39], v[126:129], v[118:121], v[36:39]
	v_mfma_f32_16x16x32_bf16 v[44:47], v[130:133], v[118:121], v[44:47]
	v_mfma_f32_16x16x32_bf16 v[24:27], v[134:137], v[118:121], v[24:27]
	ds_read_b128 v[118:121], v18 offset:34816
	s_waitcnt lgkmcnt(0)
	v_mfma_f32_16x16x32_bf16 v[56:59], v[122:125], v[118:121], v[56:59]
	v_mfma_f32_16x16x32_bf16 v[60:63], v[126:129], v[118:121], v[60:63]
	v_mfma_f32_16x16x32_bf16 v[94:97], v[130:133], v[118:121], v[94:97]
	v_mfma_f32_16x16x32_bf16 v[52:55], v[134:137], v[118:121], v[52:55]
	ds_read_b128 v[118:121], v18 offset:36864
	s_waitcnt lgkmcnt(0)
	v_mfma_f32_16x16x32_bf16 v[106:109], v[122:125], v[118:121], v[106:109]
	v_mfma_f32_16x16x32_bf16 v[110:113], v[126:129], v[118:121], v[110:113]
	v_mfma_f32_16x16x32_bf16 v[114:117], v[130:133], v[118:121], v[114:117]
	v_mfma_f32_16x16x32_bf16 v[98:101], v[134:137], v[118:121], v[98:101]
	ds_read_b128 v[118:121], v18 offset:38912
	s_waitcnt lgkmcnt(0)
	v_mfma_f32_16x16x32_bf16 v[20:23], v[122:125], v[118:121], v[20:23]
	ds_read_b128 v[122:125], v19 offset:50176
	v_mfma_f32_16x16x32_bf16 v[32:35], v[126:129], v[118:121], v[32:35]
	ds_read_b128 v[126:129], v19 offset:52224
	v_mfma_f32_16x16x32_bf16 v[40:43], v[130:133], v[118:121], v[40:43]
	ds_read_b128 v[130:133], v19 offset:54272
	v_mfma_f32_16x16x32_bf16 v[48:51], v[134:137], v[118:121], v[48:51]
	ds_read_b128 v[134:137], v19 offset:56320
	ds_read_b128 v[118:121], v18 offset:33792
	s_waitcnt lgkmcnt(0)
	v_mfma_f32_16x16x32_bf16 v[28:31], v[122:125], v[118:121], v[28:31]
	v_mfma_f32_16x16x32_bf16 v[36:39], v[126:129], v[118:121], v[36:39]
	v_mfma_f32_16x16x32_bf16 v[44:47], v[130:133], v[118:121], v[44:47]
	v_mfma_f32_16x16x32_bf16 v[24:27], v[134:137], v[118:121], v[24:27]
	ds_read_b128 v[118:121], v18 offset:35840
	s_waitcnt lgkmcnt(0)
	v_mfma_f32_16x16x32_bf16 v[56:59], v[122:125], v[118:121], v[56:59]
	v_mfma_f32_16x16x32_bf16 v[60:63], v[126:129], v[118:121], v[60:63]
	v_mfma_f32_16x16x32_bf16 v[94:97], v[130:133], v[118:121], v[94:97]
	v_mfma_f32_16x16x32_bf16 v[52:55], v[134:137], v[118:121], v[52:55]
	ds_read_b128 v[118:121], v18 offset:37888
	s_waitcnt lgkmcnt(0)
	v_mfma_f32_16x16x32_bf16 v[106:109], v[122:125], v[118:121], v[106:109]
	v_mfma_f32_16x16x32_bf16 v[110:113], v[126:129], v[118:121], v[110:113]
	v_mfma_f32_16x16x32_bf16 v[114:117], v[130:133], v[118:121], v[114:117]
	v_mfma_f32_16x16x32_bf16 v[98:101], v[134:137], v[118:121], v[98:101]
	ds_read_b128 v[118:121], v18 offset:39936
	s_waitcnt vmcnt(0)
	s_waitcnt lgkmcnt(0)
	s_barrier
	global_load_lds_dwordx4 v[64:65], off
	v_lshl_add_u64 v[64:65], v[4:5], 0, s[36:37]
	s_mov_b32 m0, s43
	s_waitcnt lgkmcnt(0)
	v_mfma_f32_16x16x32_bf16 v[20:23], v[122:125], v[118:121], v[20:23]
	global_load_lds_dwordx4 v[64:65], off
	v_lshl_add_u64 v[64:65], v[6:7], 0, s[36:37]
	s_mov_b32 m0, s50
	v_mfma_f32_16x16x32_bf16 v[32:35], v[126:129], v[118:121], v[32:35]
	global_load_lds_dwordx4 v[64:65], off
	v_lshl_add_u64 v[64:65], v[8:9], 0, s[36:37]
	s_mov_b32 m0, s51
	v_mfma_f32_16x16x32_bf16 v[40:43], v[130:133], v[118:121], v[40:43]
	global_load_lds_dwordx4 v[64:65], off
	v_lshl_add_u64 v[64:65], v[10:11], 0, s[36:37]
	s_mov_b32 m0, s52
	v_mfma_f32_16x16x32_bf16 v[48:51], v[134:137], v[118:121], v[48:51]
	global_load_lds_dwordx4 v[64:65], off
	v_lshl_add_u64 v[64:65], v[12:13], 0, s[36:37]
	s_mov_b32 m0, s53
	s_nop 0
	global_load_lds_dwordx4 v[64:65], off
	v_lshl_add_u64 v[64:65], v[14:15], 0, s[36:37]
	s_mov_b32 m0, s54
	s_nop 0
	global_load_lds_dwordx4 v[64:65], off
	v_lshl_add_u64 v[64:65], v[16:17], 0, s[36:37]
	s_mov_b32 m0, s55
	s_nop 0
	global_load_lds_dwordx4 v[64:65], off
	ds_read_b128 v[122:125], v19 offset:16384
	ds_read_b128 v[118:121], v18
	ds_read_b128 v[126:129], v19 offset:18432
	ds_read_b128 v[130:133], v19 offset:20480
	ds_read_b128 v[134:137], v19 offset:22528
	s_waitcnt lgkmcnt(0)
	v_mfma_f32_16x16x32_bf16 v[28:31], v[122:125], v[118:121], v[28:31]
	v_lshl_add_u64 v[64:65], v[2:3], 0, s[22:23]
	s_mov_b32 m0, s56
	v_lshl_add_u64 v[2:3], v[2:3], 0, s[26:27]
	v_mfma_f32_16x16x32_bf16 v[36:39], v[126:129], v[118:121], v[36:39]
	v_mfma_f32_16x16x32_bf16 v[44:47], v[130:133], v[118:121], v[44:47]
	v_mfma_f32_16x16x32_bf16 v[24:27], v[134:137], v[118:121], v[24:27]
	ds_read_b128 v[118:121], v18 offset:2048
	s_waitcnt lgkmcnt(0)
	v_mfma_f32_16x16x32_bf16 v[56:59], v[122:125], v[118:121], v[56:59]
	v_mfma_f32_16x16x32_bf16 v[60:63], v[126:129], v[118:121], v[60:63]
	v_mfma_f32_16x16x32_bf16 v[94:97], v[130:133], v[118:121], v[94:97]
	v_mfma_f32_16x16x32_bf16 v[52:55], v[134:137], v[118:121], v[52:55]
	ds_read_b128 v[118:121], v18 offset:4096
	s_waitcnt lgkmcnt(0)
	v_mfma_f32_16x16x32_bf16 v[106:109], v[122:125], v[118:121], v[106:109]
	v_mfma_f32_16x16x32_bf16 v[110:113], v[126:129], v[118:121], v[110:113]
	v_mfma_f32_16x16x32_bf16 v[114:117], v[130:133], v[118:121], v[114:117]
	v_mfma_f32_16x16x32_bf16 v[98:101], v[134:137], v[118:121], v[98:101]
	ds_read_b128 v[118:121], v18 offset:6144
	s_waitcnt lgkmcnt(0)
	v_mfma_f32_16x16x32_bf16 v[20:23], v[122:125], v[118:121], v[20:23]
	ds_read_b128 v[122:125], v19 offset:17408
	v_mfma_f32_16x16x32_bf16 v[32:35], v[126:129], v[118:121], v[32:35]
	ds_read_b128 v[126:129], v19 offset:19456
	v_mfma_f32_16x16x32_bf16 v[40:43], v[130:133], v[118:121], v[40:43]
	ds_read_b128 v[130:133], v19 offset:21504
	v_mfma_f32_16x16x32_bf16 v[48:51], v[134:137], v[118:121], v[48:51]
	ds_read_b128 v[134:137], v19 offset:23552
	ds_read_b128 v[118:121], v18 offset:1024
	s_waitcnt lgkmcnt(0)
	v_mfma_f32_16x16x32_bf16 v[28:31], v[122:125], v[118:121], v[28:31]
	v_mfma_f32_16x16x32_bf16 v[36:39], v[126:129], v[118:121], v[36:39]
	v_mfma_f32_16x16x32_bf16 v[44:47], v[130:133], v[118:121], v[44:47]
	v_mfma_f32_16x16x32_bf16 v[24:27], v[134:137], v[118:121], v[24:27]
	ds_read_b128 v[118:121], v18 offset:3072
	s_waitcnt lgkmcnt(0)
	v_mfma_f32_16x16x32_bf16 v[56:59], v[122:125], v[118:121], v[56:59]
	v_mfma_f32_16x16x32_bf16 v[60:63], v[126:129], v[118:121], v[60:63]
	v_mfma_f32_16x16x32_bf16 v[94:97], v[130:133], v[118:121], v[94:97]
	v_mfma_f32_16x16x32_bf16 v[52:55], v[134:137], v[118:121], v[52:55]
	ds_read_b128 v[118:121], v18 offset:5120
	s_waitcnt lgkmcnt(0)
	v_mfma_f32_16x16x32_bf16 v[106:109], v[122:125], v[118:121], v[106:109]
	v_mfma_f32_16x16x32_bf16 v[110:113], v[126:129], v[118:121], v[110:113]
	v_mfma_f32_16x16x32_bf16 v[114:117], v[130:133], v[118:121], v[114:117]
	v_mfma_f32_16x16x32_bf16 v[98:101], v[134:137], v[118:121], v[98:101]
	ds_read_b128 v[118:121], v18 offset:7168
	s_waitcnt vmcnt(0)
	s_waitcnt lgkmcnt(0)
	s_barrier
	global_load_lds_dwordx4 v[64:65], off
	v_lshl_add_u64 v[64:65], v[4:5], 0, s[22:23]
	s_mov_b32 m0, s57
	s_waitcnt lgkmcnt(0)
	v_mfma_f32_16x16x32_bf16 v[20:23], v[122:125], v[118:121], v[20:23]
	global_load_lds_dwordx4 v[64:65], off
	v_lshl_add_u64 v[64:65], v[6:7], 0, s[22:23]
	s_mov_b32 m0, s58
	v_mfma_f32_16x16x32_bf16 v[32:35], v[126:129], v[118:121], v[32:35]
	global_load_lds_dwordx4 v[64:65], off
	v_lshl_add_u64 v[64:65], v[8:9], 0, s[22:23]
	s_mov_b32 m0, s59
	v_mfma_f32_16x16x32_bf16 v[40:43], v[130:133], v[118:121], v[40:43]
	global_load_lds_dwordx4 v[64:65], off
	v_lshl_add_u64 v[64:65], v[10:11], 0, s[22:23]
	s_mov_b32 m0, s60
	v_mfma_f32_16x16x32_bf16 v[48:51], v[134:137], v[118:121], v[48:51]
	global_load_lds_dwordx4 v[64:65], off
	v_lshl_add_u64 v[64:65], v[12:13], 0, s[22:23]
	s_mov_b32 m0, s61
	s_nop 0
	global_load_lds_dwordx4 v[64:65], off
	v_lshl_add_u64 v[64:65], v[14:15], 0, s[22:23]
	s_mov_b32 m0, s97
	s_nop 0
	global_load_lds_dwordx4 v[64:65], off
	v_lshl_add_u64 v[64:65], v[16:17], 0, s[22:23]
	s_mov_b32 m0, s44
	s_mov_b32 s44, 7
	global_load_lds_dwordx4 v[64:65], off
	ds_read_b128 v[122:125], v19 offset:49152
	ds_read_b128 v[118:121], v18 offset:32768
	ds_read_b128 v[126:129], v19 offset:51200
	ds_read_b128 v[130:133], v19 offset:53248
	ds_read_b128 v[134:137], v19 offset:55296
	s_waitcnt lgkmcnt(0)
	v_mfma_f32_16x16x32_bf16 v[28:31], v[122:125], v[118:121], v[28:31]
	s_mov_b32 m0, s42
	v_mfma_f32_16x16x32_bf16 v[36:39], v[126:129], v[118:121], v[36:39]
	v_mfma_f32_16x16x32_bf16 v[44:47], v[130:133], v[118:121], v[44:47]
	v_mfma_f32_16x16x32_bf16 v[24:27], v[134:137], v[118:121], v[24:27]
	ds_read_b128 v[118:121], v18 offset:34816
	s_waitcnt lgkmcnt(0)
	v_mfma_f32_16x16x32_bf16 v[56:59], v[122:125], v[118:121], v[56:59]
	v_mfma_f32_16x16x32_bf16 v[60:63], v[126:129], v[118:121], v[60:63]
	v_mfma_f32_16x16x32_bf16 v[94:97], v[130:133], v[118:121], v[94:97]
	v_mfma_f32_16x16x32_bf16 v[52:55], v[134:137], v[118:121], v[52:55]
	ds_read_b128 v[118:121], v18 offset:36864
	s_waitcnt lgkmcnt(0)
	v_mfma_f32_16x16x32_bf16 v[106:109], v[122:125], v[118:121], v[106:109]
	v_mfma_f32_16x16x32_bf16 v[110:113], v[126:129], v[118:121], v[110:113]
	v_mfma_f32_16x16x32_bf16 v[114:117], v[130:133], v[118:121], v[114:117]
	v_mfma_f32_16x16x32_bf16 v[98:101], v[134:137], v[118:121], v[98:101]
	ds_read_b128 v[118:121], v18 offset:38912
	s_waitcnt lgkmcnt(0)
	v_mfma_f32_16x16x32_bf16 v[20:23], v[122:125], v[118:121], v[20:23]
	ds_read_b128 v[122:125], v19 offset:50176
	v_mfma_f32_16x16x32_bf16 v[32:35], v[126:129], v[118:121], v[32:35]
	ds_read_b128 v[126:129], v19 offset:52224
	v_mfma_f32_16x16x32_bf16 v[40:43], v[130:133], v[118:121], v[40:43]
	ds_read_b128 v[130:133], v19 offset:54272
	v_mfma_f32_16x16x32_bf16 v[48:51], v[134:137], v[118:121], v[48:51]
	ds_read_b128 v[134:137], v19 offset:56320
	ds_read_b128 v[118:121], v18 offset:33792
	s_waitcnt lgkmcnt(0)
	v_mfma_f32_16x16x32_bf16 v[28:31], v[122:125], v[118:121], v[28:31]
	v_mfma_f32_16x16x32_bf16 v[36:39], v[126:129], v[118:121], v[36:39]
	v_mfma_f32_16x16x32_bf16 v[44:47], v[130:133], v[118:121], v[44:47]
	v_mfma_f32_16x16x32_bf16 v[24:27], v[134:137], v[118:121], v[24:27]
	ds_read_b128 v[118:121], v18 offset:35840
	s_waitcnt lgkmcnt(0)
	v_mfma_f32_16x16x32_bf16 v[56:59], v[122:125], v[118:121], v[56:59]
	v_mfma_f32_16x16x32_bf16 v[60:63], v[126:129], v[118:121], v[60:63]
	v_mfma_f32_16x16x32_bf16 v[94:97], v[130:133], v[118:121], v[94:97]
	v_mfma_f32_16x16x32_bf16 v[52:55], v[134:137], v[118:121], v[52:55]
	ds_read_b128 v[118:121], v18 offset:37888
	s_waitcnt lgkmcnt(0)
	v_mfma_f32_16x16x32_bf16 v[106:109], v[122:125], v[118:121], v[106:109]
	v_mfma_f32_16x16x32_bf16 v[110:113], v[126:129], v[118:121], v[110:113]
	v_mfma_f32_16x16x32_bf16 v[114:117], v[130:133], v[118:121], v[114:117]
	v_mfma_f32_16x16x32_bf16 v[98:101], v[134:137], v[118:121], v[98:101]
	ds_read_b128 v[118:121], v18 offset:39936
	s_waitcnt vmcnt(0)
	s_waitcnt lgkmcnt(0)
	s_barrier
	global_load_lds_dwordx4 v[2:3], off
	v_lshl_add_u64 v[2:3], v[4:5], 0, s[26:27]
	s_mov_b32 m0, s43
	s_waitcnt lgkmcnt(0)
	v_mfma_f32_16x16x32_bf16 v[20:23], v[122:125], v[118:121], v[20:23]
	global_load_lds_dwordx4 v[2:3], off
	v_lshl_add_u64 v[2:3], v[6:7], 0, s[26:27]
	s_mov_b32 m0, s50
	v_mfma_f32_16x16x32_bf16 v[32:35], v[126:129], v[118:121], v[32:35]
	global_load_lds_dwordx4 v[2:3], off
	v_lshl_add_u64 v[2:3], v[8:9], 0, s[26:27]
	s_mov_b32 m0, s51
	v_mfma_f32_16x16x32_bf16 v[6:9], v[134:137], v[118:121], v[48:51]
	global_load_lds_dwordx4 v[2:3], off
	v_lshl_add_u64 v[2:3], v[10:11], 0, s[26:27]
	s_mov_b32 m0, s52
	v_mfma_f32_16x16x32_bf16 v[40:43], v[130:133], v[118:121], v[40:43]
	global_load_lds_dwordx4 v[2:3], off
	v_lshl_add_u64 v[2:3], v[12:13], 0, s[26:27]
	s_mov_b32 m0, s53
	s_mov_b32 s50, 0x40000
	global_load_lds_dwordx4 v[2:3], off
	v_lshl_add_u64 v[2:3], v[14:15], 0, s[26:27]
	s_mov_b32 m0, s54
	s_mov_b64 s[42:43], 0
	global_load_lds_dwordx4 v[2:3], off
	v_lshl_add_u64 v[2:3], v[16:17], 0, s[26:27]
	s_mov_b32 m0, s55
	s_movk_i32 s51, 0x200
	global_load_lds_dwordx4 v[2:3], off
	ds_read_b128 v[2:5], v19 offset:16384
	ds_read_b128 v[10:13], v18
	s_waitcnt lgkmcnt(0)
	v_mfma_f32_16x16x32_bf16 v[14:17], v[2:5], v[10:13], v[28:31]
	s_nop 2
	ds_read_b128 v[28:31], v19 offset:18432
	ds_read_b128 v[48:51], v19 offset:20480
	ds_read_b128 v[156:159], v19 offset:19456
	s_waitcnt lgkmcnt(0)
	v_mfma_f32_16x16x32_bf16 v[118:121], v[48:51], v[10:13], v[44:47]
	s_nop 2
	ds_read_b128 v[44:47], v19 offset:22528
	ds_read_b128 v[160:163], v19 offset:21504
	ds_read_b128 v[138:141], v19 offset:17408
	v_mfma_f32_16x16x32_bf16 v[36:39], v[28:31], v[10:13], v[36:39]
	s_waitcnt lgkmcnt(0)
	v_mfma_f32_16x16x32_bf16 v[10:13], v[44:47], v[10:13], v[24:27]
	s_nop 2
	ds_read_b128 v[24:27], v18 offset:2048
	s_waitcnt lgkmcnt(0)
	v_mfma_f32_16x16x32_bf16 v[122:125], v[2:5], v[24:27], v[56:59]
	v_mfma_f32_16x16x32_bf16 v[126:129], v[28:31], v[24:27], v[60:63]
	v_mfma_f32_16x16x32_bf16 v[94:97], v[48:51], v[24:27], v[94:97]
	v_mfma_f32_16x16x32_bf16 v[24:27], v[44:47], v[24:27], v[52:55]
	s_nop 2
	ds_read_b128 v[52:55], v18 offset:4096
	s_waitcnt lgkmcnt(0)
	v_mfma_f32_16x16x32_bf16 v[106:109], v[2:5], v[52:55], v[106:109]
	v_mfma_f32_16x16x32_bf16 v[110:113], v[28:31], v[52:55], v[110:113]
	v_mfma_f32_16x16x32_bf16 v[114:117], v[48:51], v[52:55], v[114:117]
	v_mfma_f32_16x16x32_bf16 v[98:101], v[44:47], v[52:55], v[98:101]
	ds_read_b128 v[52:55], v18 offset:6144
	s_waitcnt lgkmcnt(0)
	v_mfma_f32_16x16x32_bf16 v[152:155], v[44:47], v[52:55], v[6:9]
	s_nop 2
	ds_read_b128 v[6:9], v18 offset:1024
	s_waitcnt lgkmcnt(0)
	v_mfma_f32_16x16x32_bf16 v[58:61], v[160:163], v[6:9], v[118:121]
	s_nop 2
	ds_read_b128 v[118:121], v19 offset:23552
	v_mfma_f32_16x16x32_bf16 v[2:5], v[2:5], v[52:55], v[20:23]
	v_mfma_f32_16x16x32_bf16 v[130:133], v[28:31], v[52:55], v[32:35]
	v_mfma_f32_16x16x32_bf16 v[134:137], v[48:51], v[52:55], v[40:43]
	v_mfma_f32_16x16x32_bf16 v[46:49], v[138:141], v[6:9], v[14:17]
	v_mfma_f32_16x16x32_bf16 v[50:53], v[156:159], v[6:9], v[36:39]
	s_waitcnt lgkmcnt(0)
	v_mfma_f32_16x16x32_bf16 v[62:65], v[118:121], v[6:9], v[10:13]
	ds_read_b128 v[6:9], v18 offset:3072
	s_waitcnt lgkmcnt(0)
	v_mfma_f32_16x16x32_bf16 v[54:57], v[138:141], v[6:9], v[122:125]
	v_mfma_f32_16x16x32_bf16 v[34:37], v[156:159], v[6:9], v[126:129]
	v_mfma_f32_16x16x32_bf16 v[30:33], v[160:163], v[6:9], v[94:97]
	v_mfma_f32_16x16x32_bf16 v[22:25], v[118:121], v[6:9], v[24:27]
	ds_read_b128 v[6:9], v18 offset:5120
	s_nop 0
	v_lshl_add_u64 v[94:95], v[86:87], 0, s[2:3]
	v_lshl_add_u64 v[96:97], v[88:89], 0, s[2:3]
	s_waitcnt lgkmcnt(0)
	v_mfma_f32_16x16x32_bf16 v[38:41], v[138:141], v[6:9], v[106:109]
	s_nop 2
	ds_read_b128 v[106:109], v18 offset:7168
	v_mfma_f32_16x16x32_bf16 v[14:17], v[156:159], v[6:9], v[110:113]
	v_mfma_f32_16x16x32_bf16 v[10:13], v[160:163], v[6:9], v[114:117]
	v_mfma_f32_16x16x32_bf16 v[6:9], v[118:121], v[6:9], v[98:101]
	s_waitcnt lgkmcnt(0)
	v_mfma_f32_16x16x32_bf16 v[42:45], v[138:141], v[106:109], v[2:5]
	s_nop 0
	v_lshl_add_u64 v[98:99], v[90:91], 0, s[2:3]
	v_lshl_add_u64 v[100:101], v[92:93], 0, s[2:3]
	v_mfma_f32_16x16x32_bf16 v[18:21], v[156:159], v[106:109], v[130:133]
	v_mfma_f32_16x16x32_bf16 v[26:29], v[160:163], v[106:109], v[134:137]
	v_mfma_f32_16x16x32_bf16 v[2:5], v[118:121], v[106:109], v[152:155]
	s_branch .LBB0_63
	.p2align 8
	s_nop 0
	s_nop 0
	s_nop 0
	s_nop 0
	s_nop 0
	s_nop 0
	s_nop 0
	s_nop 0
	s_nop 0
	s_nop 0

.LBB0_63:
	s_waitcnt vmcnt(0)
	s_waitcnt lgkmcnt(0)
	s_barrier
	s_cmpk_eq_i32 s42, 0x400
	s_cbranch_scc1 .LBB0_62
	s_cmp_lt_u32 s44, 11
	s_movk_i32 s2, 0x300
	s_cselect_b32 s2, s2, 0x500
	s_add_i32 s2, s2, s51
	s_lshl_b64 s[52:53], s[2:3], 1
	s_add_u32 s52, s10, s52
	s_addc_u32 s53, s11, s53
	s_and_b32 s2, s50, 0x8000
	v_add_u32_e32 v108, s2, v1
	v_add_u32_e32 v109, 0x4000, v108
	v_readfirstlane_b32 s2, v108
	s_mov_b32 m0, s2
	v_lshl_add_u64 v[106:107], v[66:67], 1, s[52:53]
	global_load_lds_dwordx4 v[106:107], off
	s_add_u32 m0, s2, 0x4000
	v_lshl_add_u64 v[106:107], v[94:95], 0, s[42:43]
	global_load_lds_dwordx4 v[106:107], off
	s_add_u32 m0, s2, 0x1000
	v_lshl_add_u64 v[106:107], v[70:71], 1, s[52:53]
	global_load_lds_dwordx4 v[106:107], off
	s_add_u32 m0, s2, 0x5000
	v_lshl_add_u64 v[106:107], v[96:97], 0, s[42:43]
	global_load_lds_dwordx4 v[106:107], off
	s_add_u32 m0, s2, 0x2000
	v_lshl_add_u64 v[106:107], v[74:75], 1, s[52:53]
	global_load_lds_dwordx4 v[106:107], off
	s_add_u32 m0, s2, 0x6000
	v_lshl_add_u64 v[106:107], v[98:99], 0, s[42:43]
	global_load_lds_dwordx4 v[106:107], off
	s_add_u32 m0, s2, 0x3000
	v_lshl_add_u64 v[106:107], v[78:79], 1, s[52:53]
	global_load_lds_dwordx4 v[106:107], off
	s_add_u32 m0, s2, 0x7000
	v_lshl_add_u64 v[106:107], v[100:101], 0, s[42:43]
	global_load_lds_dwordx4 v[106:107], off
	s_branch .LBB0_62
